# XCD-local sync leader releases its XCD (XGEN add) before issuing its own L1 invalidate; the invalidate still completes before the leader's closing barrier (s7.2 wait placement on the release path, 7 s
# speedup vs baseline: 1.0053x; 1.0014x over previous
; __device__ __forceinline__ unsigned xb_ld(unsigned* p)              { return __hip_atomic_load(p, __ATOMIC_RELAXED, __HIP_MEMORY_SCOPE_AGENT); }
; __device__ __forceinline__ unsigned xb_add(unsigned* p, unsigned v) { return __hip_atomic_fetch_add(p, v, __ATOMIC_RELAXED, __HIP_MEMORY_SCOPE_AGENT); }
; #define XB_SPIN(cond, bar) do { unsigned _sp = 0; while (cond) { __builtin_amdgcn_s_sleep(1); \
;     if ((++_sp & 255u) == 0u) { if (xb_ld(&(bar)[XB_TMO])) break; if (_sp > XB_SPIN_CAP) { atomicAdd(&(bar)[XB_TMO], 1u); break; } } } } while (0)
; __device__ __forceinline__ void xcd_barrier(const XcdBarrier& b) {
;     ...
;     if (b.tid == 0u) {
;         unsigned* bar = b.bar;
;         __builtin_amdgcn_s_waitcnt(0);
;         unsigned nloc = b.st[0], nx = b.st[1];
;         if (nloc == 0u) { xcd_barrier_complete(bar, b.x, nloc, nx); b.st[0] = nloc; b.st[1] = nx; }
;         const unsigned old = xb_add(&bar[XB_XSUB(b.x)], 1u);
;         const unsigned gen = old / nloc;
;         if (old + 1u == (gen + 1u) * nloc) {
;             __builtin_amdgcn_fence(__ATOMIC_RELEASE, "agent");
;             asm volatile("s_waitcnt vmcnt(0)" ::: "memory");
;             const unsigned og = xb_add(&bar[XB_TOP], 1u);
;             const unsigned tg = og / nx;
;             if (og + 1u == (tg + 1u) * nx) xb_add(&bar[XB_TOPGEN], 1u);
;             else XB_SPIN(xb_ld(&bar[XB_TOPGEN]) == tg, bar);
;             __builtin_amdgcn_fence(__ATOMIC_ACQUIRE, "agent");
;             xb_add(&bar[XB_XGEN(b.x)], 1u);
;             asm volatile("s_waitcnt vmcnt(0)" ::: "memory");
.LBB0_3204:
	s_andn2_saveexec_b64 s[10:11], s[10:11]
	s_cbranch_execz .LBB0_3224
	s_mov_b64 s[10:11], exec
	v_readlane_b32 vcc_lo, v254, 42
	s_nop 0
	s_cmp_eq_u32 vcc_lo, 0
	s_cbranch_scc1 .Lmy_gsync_4
	s_branch .Lmy_lsync_4

; __device__ __forceinline__ unsigned xb_ld(unsigned* p)              { return __hip_atomic_load(p, __ATOMIC_RELAXED, __HIP_MEMORY_SCOPE_AGENT); }
; __device__ __forceinline__ unsigned xb_add(unsigned* p, unsigned v) { return __hip_atomic_fetch_add(p, v, __ATOMIC_RELAXED, __HIP_MEMORY_SCOPE_AGENT); }
; #define XB_SPIN(cond, bar) do { unsigned _sp = 0; while (cond) { __builtin_amdgcn_s_sleep(1); \
;     if ((++_sp & 255u) == 0u) { if (xb_ld(&(bar)[XB_TMO])) break; if (_sp > XB_SPIN_CAP) { atomicAdd(&(bar)[XB_TMO], 1u); break; } } } } while (0)
; __device__ __forceinline__ void xcd_barrier(const XcdBarrier& b) {
;     ...
;             __builtin_amdgcn_fence(__ATOMIC_ACQUIRE, "agent");
;             xb_add(&bar[XB_XGEN(b.x)], 1u);
;             asm volatile("s_waitcnt vmcnt(0)" ::: "memory");
;         } else {
;             XB_SPIN(xb_ld(&bar[XB_XGEN(b.x)]) == gen, bar);
;             __builtin_amdgcn_fence(__ATOMIC_ACQUIRE, "agent");
;             asm volatile("s_waitcnt vmcnt(0)" ::: "memory");
;         }
;     }
;     __syncthreads();
.LBB0_3223:
	s_or_b64 exec, exec, s[10:11]
	buffer_inv sc1
	s_waitcnt vmcnt(0)

; __device__ __forceinline__ unsigned xb_ld(unsigned* p)              { return __hip_atomic_load(p, __ATOMIC_RELAXED, __HIP_MEMORY_SCOPE_AGENT); }
; __device__ __forceinline__ unsigned xb_add(unsigned* p, unsigned v) { return __hip_atomic_fetch_add(p, v, __ATOMIC_RELAXED, __HIP_MEMORY_SCOPE_AGENT); }
; #define XB_SPIN(cond, bar) do { unsigned _sp = 0; while (cond) { __builtin_amdgcn_s_sleep(1); \
;     if ((++_sp & 255u) == 0u) { if (xb_ld(&(bar)[XB_TMO])) break; if (_sp > XB_SPIN_CAP) { atomicAdd(&(bar)[XB_TMO], 1u); break; } } } } while (0)
; __device__ __forceinline__ void xcd_barrier(const XcdBarrier& b) {
;     ...
;     if (b.tid == 0u) {
;         unsigned* bar = b.bar;
;         __builtin_amdgcn_s_waitcnt(0);
;         unsigned nloc = b.st[0], nx = b.st[1];
;         if (nloc == 0u) { xcd_barrier_complete(bar, b.x, nloc, nx); b.st[0] = nloc; b.st[1] = nx; }
;         const unsigned old = xb_add(&bar[XB_XSUB(b.x)], 1u);
;         const unsigned gen = old / nloc;
;         if (old + 1u == (gen + 1u) * nloc) {
;             __builtin_amdgcn_fence(__ATOMIC_RELEASE, "agent");
;             asm volatile("s_waitcnt vmcnt(0)" ::: "memory");
;             const unsigned og = xb_add(&bar[XB_TOP], 1u);
;             const unsigned tg = og / nx;
;             if (og + 1u == (tg + 1u) * nx) xb_add(&bar[XB_TOPGEN], 1u);
;             else XB_SPIN(xb_ld(&bar[XB_TOPGEN]) == tg, bar);
;             __builtin_amdgcn_fence(__ATOMIC_ACQUIRE, "agent");
;             xb_add(&bar[XB_XGEN(b.x)], 1u);
;             asm volatile("s_waitcnt vmcnt(0)" ::: "memory");
.LBB0_3856:
	s_andn2_saveexec_b64 s[6:7], s[6:7]
	s_cbranch_execz .LBB0_3876
	s_mov_b64 s[6:7], exec
	v_readlane_b32 vcc_lo, v254, 42
	s_nop 0
	s_cmp_eq_u32 vcc_lo, 0
	s_cbranch_scc1 .Lmy_gsync_8
	s_branch .Lmy_lsync_8

; __device__ __forceinline__ unsigned xb_ld(unsigned* p)              { return __hip_atomic_load(p, __ATOMIC_RELAXED, __HIP_MEMORY_SCOPE_AGENT); }
; __device__ __forceinline__ unsigned xb_add(unsigned* p, unsigned v) { return __hip_atomic_fetch_add(p, v, __ATOMIC_RELAXED, __HIP_MEMORY_SCOPE_AGENT); }
; #define XB_SPIN(cond, bar) do { unsigned _sp = 0; while (cond) { __builtin_amdgcn_s_sleep(1); \
;     if ((++_sp & 255u) == 0u) { if (xb_ld(&(bar)[XB_TMO])) break; if (_sp > XB_SPIN_CAP) { atomicAdd(&(bar)[XB_TMO], 1u); break; } } } } while (0)
; __device__ __forceinline__ void xcd_barrier(const XcdBarrier& b) {
;     ...
;             __builtin_amdgcn_fence(__ATOMIC_ACQUIRE, "agent");
;             xb_add(&bar[XB_XGEN(b.x)], 1u);
;             asm volatile("s_waitcnt vmcnt(0)" ::: "memory");
;         } else {
;             XB_SPIN(xb_ld(&bar[XB_XGEN(b.x)]) == gen, bar);
;             __builtin_amdgcn_fence(__ATOMIC_ACQUIRE, "agent");
;             asm volatile("s_waitcnt vmcnt(0)" ::: "memory");
;         }
;     }
;     __syncthreads();
.LBB0_3875:
	s_or_b64 exec, exec, s[6:7]
	buffer_inv sc1
	s_waitcnt vmcnt(0)
